# GLA stage3: the 64 serialized state-fragment loads per unit prefetched 12 deep into free VGPRs (counted vmcnt)
# baseline (speedup 1.0000x reference)
.LBB0_624:
	s_or_b64 exec, exec, s[0:1]
	s_add_i32 s0, 0, 0x18000
	v_add_u32_e32 v32, s0, v113
	s_waitcnt lgkmcnt(0)
	s_barrier
	ds_read_b128 v[28:31], v134
	ds_read_b128 v[24:27], v135
	ds_read_b128 v[20:23], v136
	ds_read_b128 v[16:19], v137
	ds_read_b128 v[12:15], v134 offset:16384
	ds_read_b128 v[8:11], v135 offset:16384
	ds_read_b128 v[4:7], v136 offset:16384
	ds_read_b128 v[0:3], v137 offset:16384
	ds_read_b128 v[32:35], v32
	v_add_u32_e32 v48, s0, v115
	ds_read_b128 v[48:51], v48
	v_add_u32_e32 v36, s0, v114
	ds_read_b128 v[36:39], v36
	s_waitcnt lgkmcnt(2)
	v_mfma_f32_16x16x32_bf16 v[32:35], v[32:35], v[28:31], 0
	v_add_u32_e32 v52, s0, v123
	ds_read_b128 v[52:55], v52
	s_add_i32 s1, 0, 0x1c000
	s_waitcnt lgkmcnt(2)
	v_mfma_f32_16x16x32_bf16 v[32:35], v[48:51], v[24:27], v[32:35]
	v_add_u32_e32 v48, s0, v116
	ds_read_b128 v[48:51], v48
	v_add_u32_e32 v40, s1, v113
	s_waitcnt lgkmcnt(2)
	v_mfma_f32_16x16x32_bf16 v[36:39], v[36:39], v[28:31], 0
	ds_read_b128 v[40:43], v40
	v_add_u32_e32 v44, s1, v114
	ds_read_b128 v[44:47], v44
	s_waitcnt lgkmcnt(2)
	v_mfma_f32_16x16x32_bf16 v[36:39], v[48:51], v[24:27], v[36:39]
	v_add_u32_e32 v48, s1, v115
	ds_read_b128 v[48:51], v48
	s_ashr_i32 s55, s54, 31
	s_waitcnt lgkmcnt(2)
	v_mfma_f32_16x16x32_bf16 v[40:43], v[40:43], v[12:15], 0
	s_waitcnt lgkmcnt(0)
	v_mfma_f32_16x16x32_bf16 v[40:43], v[48:51], v[8:11], v[40:43]
	v_add_u32_e32 v48, s1, v116
	ds_read_b128 v[48:51], v48
	v_mfma_f32_16x16x32_bf16 v[44:47], v[44:47], v[12:15], 0
	s_waitcnt lgkmcnt(0)
	v_mfma_f32_16x16x32_bf16 v[44:47], v[48:51], v[8:11], v[44:47]
	v_add_u32_e32 v48, s0, v117
	ds_read_b128 v[48:51], v48
	s_waitcnt lgkmcnt(0)
	v_mfma_f32_16x16x32_bf16 v[32:35], v[48:51], v[20:23], v[32:35]
	v_add_u32_e32 v48, s0, v118
	ds_read_b128 v[48:51], v48
	s_waitcnt lgkmcnt(0)
	v_mfma_f32_16x16x32_bf16 v[36:39], v[48:51], v[20:23], v[36:39]
	v_add_u32_e32 v48, s1, v117
	ds_read_b128 v[48:51], v48
	s_waitcnt lgkmcnt(0)
	v_mfma_f32_16x16x32_bf16 v[40:43], v[48:51], v[4:7], v[40:43]
	v_add_u32_e32 v48, s1, v118
	ds_read_b128 v[48:51], v48
	s_waitcnt lgkmcnt(0)
	v_mfma_f32_16x16x32_bf16 v[44:47], v[48:51], v[4:7], v[44:47]
	v_add_u32_e32 v48, s0, v119
	ds_read_b128 v[48:51], v48
	s_waitcnt lgkmcnt(0)
	v_mfma_f32_16x16x32_bf16 v[32:35], v[48:51], v[16:19], v[32:35]
	v_add_u32_e32 v48, s0, v120
	ds_read_b128 v[48:51], v48
	s_waitcnt lgkmcnt(0)
	v_mfma_f32_16x16x32_bf16 v[36:39], v[48:51], v[16:19], v[36:39]
	v_add_u32_e32 v48, s1, v119
	ds_read_b128 v[48:51], v48
	s_waitcnt lgkmcnt(0)
	v_mfma_f32_16x16x32_bf16 v[40:43], v[48:51], v[0:3], v[40:43]
	v_add_u32_e32 v48, s1, v120
	ds_read_b128 v[48:51], v48
	s_nop 5
	v_cndmask_b32_e64 v32, v32, v40, s[12:13]
	v_cndmask_b32_e64 v33, v41, v33, s[14:15]
	v_cndmask_b32_e64 v34, v34, v42, s[16:17]
	v_cndmask_b32_e64 v35, v35, v43, s[18:19]
	v_cvt_pk_bf16_f32 v40, v32, v33
	v_add_u32_e32 v32, s0, v121
	v_cvt_pk_bf16_f32 v41, v34, v35
	ds_read_b128 v[32:35], v32
	s_waitcnt lgkmcnt(1)
	v_mfma_f32_16x16x32_bf16 v[44:47], v[48:51], v[0:3], v[44:47]
	v_add_u32_e32 v48, s1, v122
	ds_read_b128 v[48:51], v48
	s_waitcnt lgkmcnt(0)
	v_mfma_f32_16x16x32_bf16 v[48:51], v[48:51], v[12:15], 0
	s_nop 3
	v_cndmask_b32_e64 v36, v36, v44, s[20:21]
	v_cndmask_b32_e64 v37, v37, v45, s[22:23]
	v_cndmask_b32_e64 v38, v38, v46, s[24:25]
	v_cndmask_b32_e64 v39, v39, v47, s[26:27]
	v_cvt_pk_bf16_f32 v42, v36, v37
	v_add_u32_e32 v36, s0, v122
	v_cvt_pk_bf16_f32 v43, v38, v39
	ds_read_b128 v[36:39], v36
	v_mfma_f32_16x16x32_bf16 v[32:35], v[32:35], v[28:31], 0
	v_add_u32_e32 v44, s1, v121
	ds_read_b128 v[44:47], v44
	v_mfma_f32_16x16x32_bf16 v[32:35], v[52:55], v[24:27], v[32:35]
	v_add_u32_e32 v52, s0, v124
	ds_read_b128 v[52:55], v52
	s_waitcnt lgkmcnt(2)
	v_mfma_f32_16x16x32_bf16 v[36:39], v[36:39], v[28:31], 0
	s_waitcnt lgkmcnt(0)
	v_mfma_f32_16x16x32_bf16 v[36:39], v[52:55], v[24:27], v[36:39]
	v_add_u32_e32 v52, s1, v123
	ds_read_b128 v[52:55], v52
	v_mfma_f32_16x16x32_bf16 v[44:47], v[44:47], v[12:15], 0
	s_waitcnt lgkmcnt(0)
	v_mfma_f32_16x16x32_bf16 v[44:47], v[52:55], v[8:11], v[44:47]
	v_add_u32_e32 v52, s1, v124
	ds_read_b128 v[52:55], v52
	s_waitcnt lgkmcnt(0)
	v_mfma_f32_16x16x32_bf16 v[48:51], v[52:55], v[8:11], v[48:51]
	v_add_u32_e32 v52, s0, v125
	ds_read_b128 v[52:55], v52
	s_waitcnt lgkmcnt(0)
	v_mfma_f32_16x16x32_bf16 v[32:35], v[52:55], v[20:23], v[32:35]
	v_add_u32_e32 v52, s0, v126
	ds_read_b128 v[52:55], v52
	s_waitcnt lgkmcnt(0)
	v_mfma_f32_16x16x32_bf16 v[36:39], v[52:55], v[20:23], v[36:39]
	v_add_u32_e32 v52, s1, v125
	ds_read_b128 v[52:55], v52
	s_waitcnt lgkmcnt(0)
	v_mfma_f32_16x16x32_bf16 v[44:47], v[52:55], v[4:7], v[44:47]
	v_add_u32_e32 v52, s1, v126
	ds_read_b128 v[52:55], v52
	s_waitcnt lgkmcnt(0)
	v_mfma_f32_16x16x32_bf16 v[48:51], v[52:55], v[4:7], v[48:51]
	v_add_u32_e32 v52, s0, v127
	ds_read_b128 v[52:55], v52
	s_waitcnt lgkmcnt(0)
	v_mfma_f32_16x16x32_bf16 v[32:35], v[52:55], v[16:19], v[32:35]
	v_add_u32_e32 v52, s0, v128
	ds_read_b128 v[52:55], v52
	s_waitcnt lgkmcnt(0)
	v_mfma_f32_16x16x32_bf16 v[36:39], v[52:55], v[16:19], v[36:39]
	v_add_u32_e32 v52, s1, v127
	ds_read_b128 v[52:55], v52
	s_waitcnt lgkmcnt(0)
	v_mfma_f32_16x16x32_bf16 v[44:47], v[52:55], v[0:3], v[44:47]
	v_add_u32_e32 v52, s1, v128
	ds_read_b128 v[52:55], v52
	s_lshl_b64 s[0:1], s[54:55], 16
	s_waitcnt lgkmcnt(0)
	v_mfma_f32_16x16x32_bf16 v[48:51], v[52:55], v[0:3], v[48:51]
	s_nop 2
	v_cndmask_b32_e64 v32, v32, v44, s[28:29]
	v_cndmask_b32_e64 v33, v33, v45, s[30:31]
	v_cndmask_b32_e64 v34, v34, v46, s[34:35]
	v_cndmask_b32_e64 v35, v35, v47, s[36:37]
	v_cvt_pk_bf16_f32 v64, v32, v33
	v_cvt_pk_bf16_f32 v65, v34, v35
	ds_read_b64_tr_b16 v[32:33], v138
	ds_read_b64_tr_b16 v[34:35], v139
	v_cndmask_b32_e64 v36, v36, v48, s[38:39]
	v_cndmask_b32_e64 v37, v37, v49, s[40:41]
	v_cndmask_b32_e64 v38, v38, v50, s[42:43]
	v_cndmask_b32_e64 v39, v39, v51, s[44:45]
	v_cvt_pk_bf16_f32 v66, v36, v37
	v_cvt_pk_bf16_f32 v67, v38, v39
	ds_read_b64_tr_b16 v[36:37], v140
	ds_read_b64_tr_b16 v[38:39], v141
	s_waitcnt lgkmcnt(2)
	v_mfma_f32_16x16x32_bf16 v[32:35], v[32:35], v[40:43], 0
	v_lshl_add_u64 v[104:105], v[74:75], 0, s[0:1]
	v_lshl_add_u64 v[44:45], v[104:105], 0, v[76:77]
	s_mov_b64 s[0:1], 0x4000000
	s_waitcnt lgkmcnt(0)
	v_mfma_f32_16x16x32_bf16 v[32:35], v[36:39], v[64:67], v[32:35]
	v_lshl_add_u64 v[106:107], v[104:105], 0, s[0:1]
	v_lshl_add_u64 v[172:173], v[104:105], 0, v[86:87]
	v_lshl_add_u64 v[176:177], v[104:105], 0, v[88:89]
	global_load_dwordx4 v[180:183], v[44:45], off
	global_load_dwordx4 v[184:187], v[44:45], off offset:64
	global_load_dwordx4 v[192:195], v[44:45], off offset:128
	global_load_dwordx4 v[196:199], v[44:45], off offset:192
	v_lshl_add_u64 v[178:179], v[106:107], 0, v[76:77]
	global_load_dwordx4 v[200:203], v[178:179], off
	global_load_dwordx4 v[204:207], v[178:179], off offset:64
	global_load_dwordx4 v[208:211], v[178:179], off offset:128
	global_load_dwordx4 v[212:215], v[178:179], off offset:192
	v_lshl_add_u64 v[178:179], v[104:105], 0, v[78:79]
	global_load_dwordx4 v[216:219], v[178:179], off
	global_load_dwordx4 v[220:223], v[178:179], off offset:64
	global_load_dwordx4 v[224:227], v[178:179], off offset:128
	global_load_dwordx4 v[228:231], v[178:179], off offset:192
	s_waitcnt vmcnt(11)
	v_mfma_f32_16x16x32_bf16 v[32:35], v[180:183], v[28:31], v[32:35]
	v_lshl_add_u64 v[178:179], v[106:107], 0, v[78:79]
	global_load_dwordx4 v[180:183], v[178:179], off
	s_nop 0
	s_waitcnt vmcnt(11)
	v_mfma_f32_16x16x32_bf16 v[32:35], v[184:187], v[24:27], v[32:35]
	global_load_dwordx4 v[184:187], v[178:179], off offset:64
	s_nop 0
	s_waitcnt vmcnt(11)
	v_mfma_f32_16x16x32_bf16 v[32:35], v[192:195], v[20:23], v[32:35]
	global_load_dwordx4 v[192:195], v[178:179], off offset:128
	s_nop 0
	v_lshl_add_u64 v[44:45], v[106:107], 0, v[76:77]
	s_waitcnt vmcnt(11)
	v_mfma_f32_16x16x32_bf16 v[32:35], v[196:199], v[16:19], v[32:35]
	global_load_dwordx4 v[196:199], v[178:179], off offset:192
	s_nop 0
	s_waitcnt vmcnt(11)
	v_mfma_f32_16x16x32_bf16 v[32:35], v[200:203], v[12:15], v[32:35]
	v_lshl_add_u64 v[178:179], v[104:105], 0, v[80:81]
	global_load_dwordx4 v[200:203], v[178:179], off
	s_nop 0
	s_waitcnt vmcnt(11)
	v_mfma_f32_16x16x32_bf16 v[32:35], v[204:207], v[8:11], v[32:35]
	global_load_dwordx4 v[204:207], v[178:179], off offset:64
	s_nop 0
	s_waitcnt vmcnt(11)
	v_mfma_f32_16x16x32_bf16 v[32:35], v[208:211], v[4:7], v[32:35]
	global_load_dwordx4 v[208:211], v[178:179], off offset:128
	s_nop 0
	v_lshl_add_u64 v[44:45], v[104:105], 0, v[78:79]
	s_waitcnt vmcnt(11)
	v_mfma_f32_16x16x32_bf16 v[60:63], v[212:215], v[0:3], v[32:35]
	global_load_dwordx4 v[212:215], v[178:179], off offset:192
	s_nop 7
	v_mul_f32_e32 v32, v61, v61
	v_mul_f32_e32 v33, v63, v63
	v_fmac_f32_e32 v32, v60, v60
	v_fmac_f32_e32 v33, v62, v62
	v_add_f32_e32 v46, v32, v33
	ds_read_b64_tr_b16 v[32:33], v142
	ds_read_b64_tr_b16 v[34:35], v143
	ds_read_b64_tr_b16 v[36:37], v144
	ds_read_b64_tr_b16 v[38:39], v145
	s_waitcnt lgkmcnt(2)
	v_mfma_f32_16x16x32_bf16 v[32:35], v[32:35], v[40:43], 0
	s_waitcnt lgkmcnt(0)
	v_mfma_f32_16x16x32_bf16 v[32:35], v[36:39], v[64:67], v[32:35]
	s_nop 0
	s_waitcnt vmcnt(11)
	v_mfma_f32_16x16x32_bf16 v[32:35], v[216:219], v[28:31], v[32:35]
	v_lshl_add_u64 v[178:179], v[106:107], 0, v[80:81]
	global_load_dwordx4 v[216:219], v[178:179], off
	s_nop 0
	s_waitcnt vmcnt(11)
	v_mfma_f32_16x16x32_bf16 v[32:35], v[220:223], v[24:27], v[32:35]
	global_load_dwordx4 v[220:223], v[178:179], off offset:64
	s_nop 0
	s_waitcnt vmcnt(11)
	v_mfma_f32_16x16x32_bf16 v[32:35], v[224:227], v[20:23], v[32:35]
	global_load_dwordx4 v[224:227], v[178:179], off offset:128
	s_nop 0
	v_lshl_add_u64 v[44:45], v[106:107], 0, v[78:79]
	s_waitcnt vmcnt(11)
	v_mfma_f32_16x16x32_bf16 v[32:35], v[228:231], v[16:19], v[32:35]
	global_load_dwordx4 v[228:231], v[178:179], off offset:192
	s_nop 0
	s_waitcnt vmcnt(11)
	v_mfma_f32_16x16x32_bf16 v[32:35], v[180:183], v[12:15], v[32:35]
	v_lshl_add_u64 v[178:179], v[104:105], 0, v[82:83]
	global_load_dwordx4 v[180:183], v[178:179], off
	s_nop 0
	s_waitcnt vmcnt(11)
	v_mfma_f32_16x16x32_bf16 v[32:35], v[184:187], v[8:11], v[32:35]
	global_load_dwordx4 v[184:187], v[178:179], off offset:64
	s_nop 0
	s_waitcnt vmcnt(11)
	v_mfma_f32_16x16x32_bf16 v[32:35], v[192:195], v[4:7], v[32:35]
	global_load_dwordx4 v[192:195], v[178:179], off offset:128
	s_nop 0
	v_lshl_add_u64 v[44:45], v[104:105], 0, v[80:81]
	s_waitcnt vmcnt(11)
	v_mfma_f32_16x16x32_bf16 v[56:59], v[196:199], v[0:3], v[32:35]
	global_load_dwordx4 v[196:199], v[178:179], off offset:192
	s_nop 7
	v_mul_f32_e32 v32, v57, v57
	v_mul_f32_e32 v33, v59, v59
	v_fmac_f32_e32 v32, v56, v56
	v_fmac_f32_e32 v33, v58, v58
	v_add_f32_e32 v32, v32, v33
	v_add_f32_e32 v46, v46, v32
	ds_read_b64_tr_b16 v[32:33], v146
	ds_read_b64_tr_b16 v[34:35], v147
	ds_read_b64_tr_b16 v[36:37], v148
	ds_read_b64_tr_b16 v[38:39], v149
	s_waitcnt lgkmcnt(2)
	v_mfma_f32_16x16x32_bf16 v[32:35], v[32:35], v[40:43], 0
	s_waitcnt lgkmcnt(0)
	v_mfma_f32_16x16x32_bf16 v[32:35], v[36:39], v[64:67], v[32:35]
	s_nop 0
	s_waitcnt vmcnt(11)
	v_mfma_f32_16x16x32_bf16 v[32:35], v[200:203], v[28:31], v[32:35]
	v_lshl_add_u64 v[178:179], v[106:107], 0, v[82:83]
	global_load_dwordx4 v[200:203], v[178:179], off
	s_nop 0
	s_waitcnt vmcnt(11)
	v_mfma_f32_16x16x32_bf16 v[32:35], v[204:207], v[24:27], v[32:35]
	global_load_dwordx4 v[204:207], v[178:179], off offset:64
	s_nop 0
	s_waitcnt vmcnt(11)
	v_mfma_f32_16x16x32_bf16 v[32:35], v[208:211], v[20:23], v[32:35]
	global_load_dwordx4 v[208:211], v[178:179], off offset:128
	s_nop 0
	v_lshl_add_u64 v[44:45], v[106:107], 0, v[80:81]
	s_waitcnt vmcnt(11)
	v_mfma_f32_16x16x32_bf16 v[32:35], v[212:215], v[16:19], v[32:35]
	global_load_dwordx4 v[212:215], v[178:179], off offset:192
	s_nop 0
	s_waitcnt vmcnt(11)
	v_mfma_f32_16x16x32_bf16 v[32:35], v[216:219], v[12:15], v[32:35]
	v_lshl_add_u64 v[178:179], v[104:105], 0, v[84:85]
	global_load_dwordx4 v[216:219], v[178:179], off
	s_nop 0
	s_waitcnt vmcnt(11)
	v_mfma_f32_16x16x32_bf16 v[32:35], v[220:223], v[8:11], v[32:35]
	global_load_dwordx4 v[220:223], v[178:179], off offset:64
	s_nop 0
	s_waitcnt vmcnt(11)
	v_mfma_f32_16x16x32_bf16 v[32:35], v[224:227], v[4:7], v[32:35]
	global_load_dwordx4 v[224:227], v[178:179], off offset:128
	s_nop 0
	v_lshl_add_u64 v[44:45], v[104:105], 0, v[82:83]
	s_waitcnt vmcnt(11)
	v_mfma_f32_16x16x32_bf16 v[52:55], v[228:231], v[0:3], v[32:35]
	global_load_dwordx4 v[228:231], v[178:179], off offset:192
	s_nop 7
	v_mul_f32_e32 v32, v53, v53
	v_mul_f32_e32 v33, v55, v55
	v_fmac_f32_e32 v32, v52, v52
	v_fmac_f32_e32 v33, v54, v54
	v_add_f32_e32 v32, v32, v33
	v_add_f32_e32 v46, v46, v32
	ds_read_b64_tr_b16 v[32:33], v150
	ds_read_b64_tr_b16 v[34:35], v151
	ds_read_b64_tr_b16 v[36:37], v152
	ds_read_b64_tr_b16 v[38:39], v153
	s_waitcnt lgkmcnt(2)
	v_mfma_f32_16x16x32_bf16 v[32:35], v[32:35], v[40:43], 0
	s_waitcnt lgkmcnt(0)
	v_mfma_f32_16x16x32_bf16 v[32:35], v[36:39], v[64:67], v[32:35]
	s_nop 0
	s_waitcnt vmcnt(11)
	v_mfma_f32_16x16x32_bf16 v[32:35], v[180:183], v[28:31], v[32:35]
	v_lshl_add_u64 v[178:179], v[106:107], 0, v[84:85]
	global_load_dwordx4 v[180:183], v[178:179], off
	s_nop 0
	s_waitcnt vmcnt(11)
	v_mfma_f32_16x16x32_bf16 v[32:35], v[184:187], v[24:27], v[32:35]
	global_load_dwordx4 v[184:187], v[178:179], off offset:64
	s_nop 0
	s_waitcnt vmcnt(11)
	v_mfma_f32_16x16x32_bf16 v[32:35], v[192:195], v[20:23], v[32:35]
	global_load_dwordx4 v[192:195], v[178:179], off offset:128
	s_nop 0
	v_lshl_add_u64 v[44:45], v[106:107], 0, v[82:83]
	s_waitcnt vmcnt(11)
	v_mfma_f32_16x16x32_bf16 v[32:35], v[196:199], v[16:19], v[32:35]
	global_load_dwordx4 v[196:199], v[178:179], off offset:192
	s_nop 0
	s_waitcnt vmcnt(11)
	v_mfma_f32_16x16x32_bf16 v[32:35], v[200:203], v[12:15], v[32:35]
	global_load_dwordx4 v[200:203], v[172:173], off
	s_nop 0
	s_waitcnt vmcnt(11)
	v_mfma_f32_16x16x32_bf16 v[32:35], v[204:207], v[8:11], v[32:35]
	global_load_dwordx4 v[204:207], v[172:173], off offset:64
	s_nop 0
	s_waitcnt vmcnt(11)
	v_mfma_f32_16x16x32_bf16 v[32:35], v[208:211], v[4:7], v[32:35]
	global_load_dwordx4 v[208:211], v[172:173], off offset:128
	s_nop 0
	v_lshl_add_u64 v[44:45], v[104:105], 0, v[84:85]
	v_lshl_add_u64 v[104:105], v[104:105], 0, v[90:91]
	s_waitcnt vmcnt(11)
	v_mfma_f32_16x16x32_bf16 v[48:51], v[212:215], v[0:3], v[32:35]
	global_load_dwordx4 v[212:215], v[172:173], off offset:192
	s_nop 7
	v_mul_f32_e32 v32, v49, v49
	v_mul_f32_e32 v33, v51, v51
	v_fmac_f32_e32 v32, v48, v48
	v_fmac_f32_e32 v33, v50, v50
	v_add_f32_e32 v32, v32, v33
	v_add_f32_e32 v99, v46, v32
	ds_read_b64_tr_b16 v[32:33], v154
	ds_read_b64_tr_b16 v[34:35], v155
	ds_read_b64_tr_b16 v[36:37], v156
	ds_read_b64_tr_b16 v[38:39], v157
	s_waitcnt lgkmcnt(2)
	v_mfma_f32_16x16x32_bf16 v[32:35], v[32:35], v[40:43], 0
	s_waitcnt lgkmcnt(0)
	v_mfma_f32_16x16x32_bf16 v[32:35], v[36:39], v[64:67], v[32:35]
	s_nop 0
	s_waitcnt vmcnt(11)
	v_mfma_f32_16x16x32_bf16 v[32:35], v[216:219], v[28:31], v[32:35]
	v_lshl_add_u64 v[178:179], v[106:107], 0, v[86:87]
	global_load_dwordx4 v[216:219], v[178:179], off
	s_nop 0
	s_waitcnt vmcnt(11)
	v_mfma_f32_16x16x32_bf16 v[32:35], v[220:223], v[24:27], v[32:35]
	global_load_dwordx4 v[220:223], v[178:179], off offset:64
	s_nop 0
	s_waitcnt vmcnt(11)
	v_mfma_f32_16x16x32_bf16 v[32:35], v[224:227], v[20:23], v[32:35]
	global_load_dwordx4 v[224:227], v[178:179], off offset:128
	s_nop 0
	v_lshl_add_u64 v[44:45], v[106:107], 0, v[84:85]
	s_waitcnt vmcnt(11)
	v_mfma_f32_16x16x32_bf16 v[32:35], v[228:231], v[16:19], v[32:35]
	global_load_dwordx4 v[228:231], v[178:179], off offset:192
	s_nop 0
	s_waitcnt vmcnt(11)
	v_mfma_f32_16x16x32_bf16 v[32:35], v[180:183], v[12:15], v[32:35]
	global_load_dwordx4 v[180:183], v[176:177], off
	s_nop 0
	s_waitcnt vmcnt(11)
	v_mfma_f32_16x16x32_bf16 v[32:35], v[184:187], v[8:11], v[32:35]
	global_load_dwordx4 v[184:187], v[176:177], off offset:64
	s_nop 0
	s_waitcnt vmcnt(11)
	v_mfma_f32_16x16x32_bf16 v[32:35], v[192:195], v[4:7], v[32:35]
	global_load_dwordx4 v[192:195], v[176:177], off offset:128
	s_nop 0
	s_waitcnt vmcnt(11)
	v_mfma_f32_16x16x32_bf16 v[44:47], v[196:199], v[0:3], v[32:35]
	global_load_dwordx4 v[196:199], v[176:177], off offset:192
	s_nop 7
	v_mul_f32_e32 v32, v45, v45
	v_mul_f32_e32 v33, v47, v47
	v_fmac_f32_e32 v32, v44, v44
	v_fmac_f32_e32 v33, v46, v46
	v_add_f32_e32 v32, v32, v33
	v_add_f32_e32 v99, v99, v32
	ds_read_b64_tr_b16 v[32:33], v158
	ds_read_b64_tr_b16 v[34:35], v159
	ds_read_b64_tr_b16 v[36:37], v160
	ds_read_b64_tr_b16 v[38:39], v161
	s_waitcnt lgkmcnt(2)
	v_mfma_f32_16x16x32_bf16 v[32:35], v[32:35], v[40:43], 0
	s_waitcnt lgkmcnt(0)
	v_mfma_f32_16x16x32_bf16 v[32:35], v[36:39], v[64:67], v[32:35]
	s_nop 0
	s_waitcnt vmcnt(11)
	v_mfma_f32_16x16x32_bf16 v[32:35], v[200:203], v[28:31], v[32:35]
	v_lshl_add_u64 v[178:179], v[106:107], 0, v[88:89]
	global_load_dwordx4 v[200:203], v[178:179], off
	s_nop 0
	s_waitcnt vmcnt(11)
	v_mfma_f32_16x16x32_bf16 v[32:35], v[204:207], v[24:27], v[32:35]
	global_load_dwordx4 v[204:207], v[178:179], off offset:64
	s_nop 0
	s_waitcnt vmcnt(11)
	v_mfma_f32_16x16x32_bf16 v[32:35], v[208:211], v[20:23], v[32:35]
	global_load_dwordx4 v[208:211], v[178:179], off offset:128
	s_nop 0
	v_lshl_add_u64 v[172:173], v[106:107], 0, v[86:87]
	s_waitcnt vmcnt(11)
	v_mfma_f32_16x16x32_bf16 v[32:35], v[212:215], v[16:19], v[32:35]
	global_load_dwordx4 v[212:215], v[178:179], off offset:192
	s_nop 0
	s_waitcnt vmcnt(11)
	v_mfma_f32_16x16x32_bf16 v[32:35], v[216:219], v[12:15], v[32:35]
	global_load_dwordx4 v[216:219], v[104:105], off
	s_nop 0
	s_waitcnt vmcnt(11)
	v_mfma_f32_16x16x32_bf16 v[32:35], v[220:223], v[8:11], v[32:35]
	global_load_dwordx4 v[220:223], v[104:105], off offset:64
	s_nop 0
	s_waitcnt vmcnt(11)
	v_mfma_f32_16x16x32_bf16 v[32:35], v[224:227], v[4:7], v[32:35]
	global_load_dwordx4 v[224:227], v[104:105], off offset:128
	s_nop 0
	s_waitcnt vmcnt(11)
	v_mfma_f32_16x16x32_bf16 v[36:39], v[228:231], v[0:3], v[32:35]
	global_load_dwordx4 v[228:231], v[104:105], off offset:192
	s_nop 7
	v_mul_f32_e32 v32, v37, v37
	v_mul_f32_e32 v33, v39, v39
	v_fmac_f32_e32 v32, v36, v36
	v_fmac_f32_e32 v33, v38, v38
	v_add_f32_e32 v32, v32, v33
	v_add_f32_e32 v99, v99, v32
	ds_read_b64_tr_b16 v[32:33], v162
	ds_read_b64_tr_b16 v[34:35], v163
	ds_read_b64_tr_b16 v[172:173], v164
	ds_read_b64_tr_b16 v[174:175], v165
	s_waitcnt lgkmcnt(2)
	v_mfma_f32_16x16x32_bf16 v[32:35], v[32:35], v[40:43], 0
	s_waitcnt lgkmcnt(0)
	v_mfma_f32_16x16x32_bf16 v[32:35], v[172:175], v[64:67], v[32:35]
	s_nop 0
	s_waitcnt vmcnt(11)
	v_mfma_f32_16x16x32_bf16 v[32:35], v[180:183], v[28:31], v[32:35]
	v_lshl_add_u64 v[178:179], v[106:107], 0, v[90:91]
	global_load_dwordx4 v[180:183], v[178:179], off
	s_nop 0
	s_waitcnt vmcnt(11)
	v_mfma_f32_16x16x32_bf16 v[32:35], v[184:187], v[24:27], v[32:35]
	global_load_dwordx4 v[184:187], v[178:179], off offset:64
	s_nop 0
	s_waitcnt vmcnt(11)
	v_mfma_f32_16x16x32_bf16 v[32:35], v[192:195], v[20:23], v[32:35]
	global_load_dwordx4 v[192:195], v[178:179], off offset:128
	s_nop 0
	v_lshl_add_u64 v[176:177], v[106:107], 0, v[88:89]
	s_waitcnt vmcnt(11)
	v_mfma_f32_16x16x32_bf16 v[32:35], v[196:199], v[16:19], v[32:35]
	global_load_dwordx4 v[196:199], v[178:179], off offset:192
	s_nop 0
	s_waitcnt vmcnt(11)
	v_mfma_f32_16x16x32_bf16 v[32:35], v[200:203], v[12:15], v[32:35]
	s_nop 0
	s_waitcnt vmcnt(10)
	v_mfma_f32_16x16x32_bf16 v[32:35], v[204:207], v[8:11], v[32:35]
	s_nop 0
	s_waitcnt vmcnt(9)
	v_mfma_f32_16x16x32_bf16 v[32:35], v[208:211], v[4:7], v[32:35]
	s_nop 0
	s_waitcnt vmcnt(8)
	v_mfma_f32_16x16x32_bf16 v[32:35], v[212:215], v[0:3], v[32:35]
	s_nop 7
	v_mul_f32_e32 v101, v33, v33
	v_mul_f32_e32 v172, v35, v35
	v_fmac_f32_e32 v101, v32, v32
	v_fmac_f32_e32 v172, v34, v34
	v_add_f32_e32 v101, v101, v172
	ds_read_b64_tr_b16 v[172:173], v166
	ds_read_b64_tr_b16 v[174:175], v167
	s_waitcnt lgkmcnt(0)
	v_mfma_f32_16x16x32_bf16 v[40:43], v[172:175], v[40:43], 0
	ds_read_b64_tr_b16 v[172:173], v168
	ds_read_b64_tr_b16 v[174:175], v169
	v_add_f32_e32 v99, v99, v101
	s_waitcnt lgkmcnt(0)
	v_mfma_f32_16x16x32_bf16 v[40:43], v[172:175], v[64:67], v[40:43]
	s_nop 0
	s_waitcnt vmcnt(7)
	v_mov_b32_e32 v64, v216
	v_mov_b32_e32 v65, v217
	v_mov_b32_e32 v66, v218
	v_mov_b32_e32 v67, v219
	s_nop 1
	v_mfma_f32_16x16x32_bf16 v[28:31], v[64:67], v[28:31], v[40:43]
	s_nop 4
	s_nop 0
	s_waitcnt vmcnt(6)
	v_mov_b32_e32 v40, v220
	v_mov_b32_e32 v41, v221
	v_mov_b32_e32 v42, v222
	v_mov_b32_e32 v43, v223
	s_nop 1
	v_mfma_f32_16x16x32_bf16 v[24:27], v[40:43], v[24:27], v[28:31]
	s_nop 2
	s_nop 0
	s_waitcnt vmcnt(5)
	v_mov_b32_e32 v28, v224
	v_mov_b32_e32 v29, v225
	v_mov_b32_e32 v30, v226
	v_mov_b32_e32 v31, v227
	s_nop 1
	v_mfma_f32_16x16x32_bf16 v[20:23], v[28:31], v[20:23], v[24:27]
	s_nop 2
	s_nop 0
	s_waitcnt vmcnt(4)
	v_mov_b32_e32 v24, v228
	v_mov_b32_e32 v25, v229
	v_mov_b32_e32 v26, v230
	v_mov_b32_e32 v27, v231
	s_nop 1
	v_mfma_f32_16x16x32_bf16 v[16:19], v[24:27], v[16:19], v[20:23]
	v_lshl_add_u64 v[24:25], v[106:107], 0, v[90:91]
	s_nop 1
	s_nop 0
	s_waitcnt vmcnt(3)
	v_mov_b32_e32 v20, v180
	v_mov_b32_e32 v21, v181
	v_mov_b32_e32 v22, v182
	v_mov_b32_e32 v23, v183
	s_nop 1
	v_mfma_f32_16x16x32_bf16 v[12:15], v[20:23], v[12:15], v[16:19]
	s_nop 2
	s_nop 0
	s_waitcnt vmcnt(2)
	v_mov_b32_e32 v16, v184
	v_mov_b32_e32 v17, v185
	v_mov_b32_e32 v18, v186
	v_mov_b32_e32 v19, v187
	s_nop 1
	v_mfma_f32_16x16x32_bf16 v[8:11], v[16:19], v[8:11], v[12:15]
	s_nop 2
	s_nop 0
	s_waitcnt vmcnt(1)
	v_mov_b32_e32 v12, v192
	v_mov_b32_e32 v13, v193
	v_mov_b32_e32 v14, v194
	v_mov_b32_e32 v15, v195
	s_nop 1
	v_mfma_f32_16x16x32_bf16 v[4:7], v[12:15], v[4:7], v[8:11]
	s_nop 2
	s_nop 0
	s_waitcnt vmcnt(0)
	v_mov_b32_e32 v8, v196
	v_mov_b32_e32 v9, v197
	v_mov_b32_e32 v10, v198
	v_mov_b32_e32 v11, v199
	s_nop 1
	v_mfma_f32_16x16x32_bf16 v[0:3], v[8:11], v[0:3], v[4:7]
	s_nop 7
	v_mul_f32_e32 v4, v1, v1
	v_mul_f32_e32 v5, v3, v3
	v_fmac_f32_e32 v4, v0, v0
	v_fmac_f32_e32 v5, v2, v2
	v_add_f32_e32 v4, v4, v5
	v_add_f32_e32 v4, v99, v4
	ds_bpermute_b32 v5, v129, v4
	s_waitcnt lgkmcnt(0)
	v_add_f32_e32 v4, v4, v5
	ds_bpermute_b32 v5, v130, v4
	s_and_saveexec_b64 s[0:1], s[46:47]
	s_cbranch_execz .LBB0_612
	s_waitcnt lgkmcnt(0)
	v_add_f32_e32 v4, v4, v5
	ds_write_b32 v131, v4
	s_branch .LBB0_612
